# setup phase: light units rebalanced onto the blocks with two adaLN units; MLA queue claim issued one tile before the end of the tile loop
# speedup vs baseline: 1.0017x; 1.0017x over previous
.LBB0_34:
	s_add_i32 s4, s66, 0xffffffb0
	s_and_b64 s[2:3], s[6:7], exec
	s_cbranch_scc1 .Lp0_ada2
	s_mov_b32 s6, s4
	s_branch .LBB0_42
.Lp0_ada2:
	s_addk_i32 s66, 0x368
	s_movk_i32 s2, 0x50
	s_movk_i32 s3, 0x580
	s_branch .LBB0_43

.LBB0_42:
	s_movk_i32 s2, 0xb0
	s_movk_i32 s3, 0x3f8
	s_mov_b32 s66, s6

.LBB0_1213:
	s_add_i32 s2, s10, 2
	s_cmp_lg_u32 s2, s19
	s_cbranch_scc1 .Lqe3
	s_mov_b64 s[98:99], exec
	s_mov_b64 exec, s[4:5]
	s_cbranch_execz .Lqp3
	v_readlane_b32 s2, v252, 23
	v_readlane_b32 s3, v252, 24
	s_nop 1
	v_mov_b64_e32 v[254:255], s[2:3]
	global_atomic_add v253, v[254:255], v177, off sc0
.Lqp3:
	s_mov_b64 exec, s[98:99]
	s_mov_b32 s32, 1
.Lqe3:
	s_add_i32 s23, s10, 2
	s_cmp_ge_u32 s23, s19
	s_cbranch_scc1 .LBB0_1210
	s_cmp_lt_u32 s23, s18
	s_cbranch_scc0 .LBB0_1208
	s_mov_b64 s[10:11], 0xa372000
	s_mov_b64 s[12:13], 0x5d52000
	s_mov_b64 s[16:17], s[6:7]
	s_branch .LBB0_1209
.LBB0_1216:
	v_mov_b32_e32 v4, v101
	s_nop 1
	v_permlane16_swap_b32_e32 v101, v4
	v_add_f32_e32 v4, v101, v4
	v_mov_b32_e32 v5, v4
	s_nop 1
	v_permlane32_swap_b32_e32 v4, v5
	v_add_f32_e32 v4, v4, v5
	v_div_scale_f32 v5, s[6:7], v4, v4, 1.0
	v_rcp_f32_e32 v6, v5
	v_lshlrev_b32_e32 v88, 1, v97
	v_fma_f32 v7, -v5, v6, 1.0
	v_fmac_f32_e32 v6, v7, v6
	v_div_scale_f32 v7, vcc, 1.0, v4, 1.0
	v_mul_f32_e32 v8, v7, v6
	v_fma_f32 v9, -v5, v8, v7
	v_fmac_f32_e32 v8, v9, v6
	v_fma_f32 v5, -v5, v8, v7
	v_div_fmas_f32 v5, v5, v6, v8
	v_lshlrev_b64 v[6:7], 11, v[92:93]
	v_div_fixup_f32 v4, v5, v4, 1.0
	v_lshl_add_u64 v[6:7], s[48:49], 0, v[6:7]
	v_lshl_add_u64 v[6:7], v[6:7], 0, s[44:45]
	v_pk_mul_f32 v[8:9], v[68:69], v[4:5] op_sel_hi:[1,0]
	v_pk_mul_f32 v[10:11], v[70:71], v[4:5] op_sel_hi:[1,0]
	v_lshl_add_u64 v[6:7], v[6:7], 0, v[88:89]
	v_cvt_pk_bf16_f32 v8, v8, v9
	v_cvt_pk_bf16_f32 v9, v10, v11
	flat_store_dwordx2 v[6:7], v[8:9]
	v_pk_mul_f32 v[8:9], v[64:65], v[4:5] op_sel_hi:[1,0]
	v_pk_mul_f32 v[10:11], v[66:67], v[4:5] op_sel_hi:[1,0]
	v_cvt_pk_bf16_f32 v8, v8, v9
	v_cvt_pk_bf16_f32 v9, v10, v11
	flat_store_dwordx2 v[6:7], v[8:9] offset:32
	v_pk_mul_f32 v[8:9], v[72:73], v[4:5] op_sel_hi:[1,0]
	v_pk_mul_f32 v[10:11], v[74:75], v[4:5] op_sel_hi:[1,0]
	v_cvt_pk_bf16_f32 v8, v8, v9
	v_cvt_pk_bf16_f32 v9, v10, v11
	flat_store_dwordx2 v[6:7], v[8:9] offset:64
	v_pk_mul_f32 v[8:9], v[76:77], v[4:5] op_sel_hi:[1,0]
	v_mov_b32_e32 v5, v100
	s_nop 1
	v_permlane16_swap_b32_e32 v100, v5
	v_add_f32_e32 v5, v100, v5
	v_cvt_pk_bf16_f32 v8, v8, v9
	v_mov_b32_e32 v9, v5
	s_nop 1
	v_permlane32_swap_b32_e32 v5, v9
	v_add_f32_e32 v10, v5, v9
	v_div_scale_f32 v11, s[6:7], v10, v10, 1.0
	v_rcp_f32_e32 v12, v11
	v_pk_mul_f32 v[4:5], v[78:79], v[4:5] op_sel_hi:[1,0]
	s_nop 0
	v_cvt_pk_bf16_f32 v9, v4, v5
	v_fma_f32 v4, -v11, v12, 1.0
	v_fmac_f32_e32 v12, v4, v12
	v_div_scale_f32 v4, vcc, 1.0, v10, 1.0
	v_mul_f32_e32 v5, v4, v12
	flat_store_dwordx2 v[6:7], v[8:9] offset:96
	v_fma_f32 v6, -v11, v5, v4
	v_fmac_f32_e32 v5, v6, v12
	v_fma_f32 v4, -v11, v5, v4
	v_div_fmas_f32 v4, v4, v12, v5
	v_lshlrev_b64 v[6:7], 11, v[90:91]
	v_div_fixup_f32 v4, v4, v10, 1.0
	v_lshl_add_u64 v[6:7], s[48:49], 0, v[6:7]
	v_lshl_add_u64 v[6:7], v[6:7], 0, s[44:45]
	v_pk_mul_f32 v[8:9], v[52:53], v[4:5] op_sel_hi:[1,0]
	v_pk_mul_f32 v[10:11], v[54:55], v[4:5] op_sel_hi:[1,0]
	v_lshl_add_u64 v[6:7], v[6:7], 0, v[88:89]
	v_cvt_pk_bf16_f32 v8, v8, v9
	v_cvt_pk_bf16_f32 v9, v10, v11
	flat_store_dwordx2 v[6:7], v[8:9]
	v_pk_mul_f32 v[8:9], v[48:49], v[4:5] op_sel_hi:[1,0]
	v_pk_mul_f32 v[10:11], v[50:51], v[4:5] op_sel_hi:[1,0]
	v_cvt_pk_bf16_f32 v8, v8, v9
	v_cvt_pk_bf16_f32 v9, v10, v11
	flat_store_dwordx2 v[6:7], v[8:9] offset:32
	v_pk_mul_f32 v[8:9], v[56:57], v[4:5] op_sel_hi:[1,0]
	v_pk_mul_f32 v[10:11], v[58:59], v[4:5] op_sel_hi:[1,0]
	v_cvt_pk_bf16_f32 v8, v8, v9
	v_cvt_pk_bf16_f32 v9, v10, v11
	flat_store_dwordx2 v[6:7], v[8:9] offset:64
	v_pk_mul_f32 v[8:9], v[60:61], v[4:5] op_sel_hi:[1,0]
	v_pk_mul_f32 v[4:5], v[62:63], v[4:5] op_sel_hi:[1,0]
	v_cvt_pk_bf16_f32 v8, v8, v9
	v_cvt_pk_bf16_f32 v9, v4, v5
	flat_store_dwordx2 v[6:7], v[8:9] offset:96
	s_waitcnt lgkmcnt(0)
	s_barrier
	s_and_saveexec_b64 s[6:7], s[4:5]
	s_cbranch_execz .LBB0_1198
	s_cmp_eq_u32 s32, 0
	s_cbranch_scc1 .Lqf0
	s_waitcnt vmcnt(0) lgkmcnt(0)
	ds_write_b32 v178, v253
	s_mov_b32 s32, 0
	s_branch .LBB0_1198

.LBB0_2970:
	s_add_i32 s24, s10, 2
	s_cmp_lg_u32 s24, s19
	s_cbranch_scc1 .Lqe7
	s_mov_b64 s[98:99], exec
	s_mov_b64 exec, s[4:5]
	s_cbranch_execz .Lqp7
	v_readlane_b32 s24, v252, 23
	v_readlane_b32 s25, v252, 24
	s_nop 1
	v_mov_b64_e32 v[254:255], s[24:25]
	global_atomic_add v253, v[254:255], v176, off sc0
.Lqp7:
	s_mov_b64 exec, s[98:99]
	s_mov_b32 s32, 1
.Lqe7:
	s_add_i32 s10, s10, 2
	s_cmp_ge_u32 s10, s19
	s_cbranch_scc1 .LBB0_2967
	s_cmp_ge_u32 s10, s18
	s_cbranch_scc0 .LBB0_2965
	s_mov_b64 s[10:11], 0x3540000
	s_mov_b64 s[12:13], 0x3140000
	s_mov_b32 s23, s20
	s_mov_b64 s[16:17], s[8:9]
	s_branch .LBB0_2966
.LBB0_2973:
	v_mov_b32_e32 v4, v101
	s_nop 1
	v_permlane16_swap_b32_e32 v101, v4
	v_add_f32_e32 v4, v101, v4
	v_mov_b32_e32 v5, v4
	s_nop 1
	v_permlane32_swap_b32_e32 v4, v5
	v_add_f32_e32 v4, v4, v5
	v_div_scale_f32 v5, s[6:7], v4, v4, 1.0
	v_rcp_f32_e32 v6, v5
	v_lshlrev_b32_e32 v88, 1, v97
	v_fma_f32 v7, -v5, v6, 1.0
	v_fmac_f32_e32 v6, v7, v6
	v_div_scale_f32 v7, vcc, 1.0, v4, 1.0
	v_mul_f32_e32 v8, v7, v6
	v_fma_f32 v9, -v5, v8, v7
	v_fmac_f32_e32 v8, v9, v6
	v_fma_f32 v5, -v5, v8, v7
	v_div_fmas_f32 v5, v5, v6, v8
	v_lshlrev_b64 v[6:7], 11, v[92:93]
	v_div_fixup_f32 v4, v5, v4, 1.0
	v_lshl_add_u64 v[6:7], s[48:49], 0, v[6:7]
	v_lshl_add_u64 v[6:7], v[6:7], 0, s[44:45]
	v_pk_mul_f32 v[8:9], v[68:69], v[4:5] op_sel_hi:[1,0]
	v_pk_mul_f32 v[10:11], v[70:71], v[4:5] op_sel_hi:[1,0]
	v_lshl_add_u64 v[6:7], v[6:7], 0, v[88:89]
	v_cvt_pk_bf16_f32 v8, v8, v9
	v_cvt_pk_bf16_f32 v9, v10, v11
	flat_store_dwordx2 v[6:7], v[8:9]
	v_pk_mul_f32 v[8:9], v[64:65], v[4:5] op_sel_hi:[1,0]
	v_pk_mul_f32 v[10:11], v[66:67], v[4:5] op_sel_hi:[1,0]
	v_cvt_pk_bf16_f32 v8, v8, v9
	v_cvt_pk_bf16_f32 v9, v10, v11
	flat_store_dwordx2 v[6:7], v[8:9] offset:32
	v_pk_mul_f32 v[8:9], v[72:73], v[4:5] op_sel_hi:[1,0]
	v_pk_mul_f32 v[10:11], v[74:75], v[4:5] op_sel_hi:[1,0]
	v_cvt_pk_bf16_f32 v8, v8, v9
	v_cvt_pk_bf16_f32 v9, v10, v11
	flat_store_dwordx2 v[6:7], v[8:9] offset:64
	v_pk_mul_f32 v[8:9], v[76:77], v[4:5] op_sel_hi:[1,0]
	v_mov_b32_e32 v5, v100
	s_nop 1
	v_permlane16_swap_b32_e32 v100, v5
	v_add_f32_e32 v5, v100, v5
	v_cvt_pk_bf16_f32 v8, v8, v9
	v_mov_b32_e32 v9, v5
	s_nop 1
	v_permlane32_swap_b32_e32 v5, v9
	v_add_f32_e32 v10, v5, v9
	v_div_scale_f32 v11, s[6:7], v10, v10, 1.0
	v_rcp_f32_e32 v12, v11
	v_pk_mul_f32 v[4:5], v[78:79], v[4:5] op_sel_hi:[1,0]
	s_nop 0
	v_cvt_pk_bf16_f32 v9, v4, v5
	v_fma_f32 v4, -v11, v12, 1.0
	v_fmac_f32_e32 v12, v4, v12
	v_div_scale_f32 v4, vcc, 1.0, v10, 1.0
	v_mul_f32_e32 v5, v4, v12
	flat_store_dwordx2 v[6:7], v[8:9] offset:96
	v_fma_f32 v6, -v11, v5, v4
	v_fmac_f32_e32 v5, v6, v12
	v_fma_f32 v4, -v11, v5, v4
	v_div_fmas_f32 v4, v4, v12, v5
	v_lshlrev_b64 v[6:7], 11, v[90:91]
	v_div_fixup_f32 v4, v4, v10, 1.0
	v_lshl_add_u64 v[6:7], s[48:49], 0, v[6:7]
	v_lshl_add_u64 v[6:7], v[6:7], 0, s[44:45]
	v_pk_mul_f32 v[8:9], v[52:53], v[4:5] op_sel_hi:[1,0]
	v_pk_mul_f32 v[10:11], v[54:55], v[4:5] op_sel_hi:[1,0]
	v_lshl_add_u64 v[6:7], v[6:7], 0, v[88:89]
	v_cvt_pk_bf16_f32 v8, v8, v9
	v_cvt_pk_bf16_f32 v9, v10, v11
	flat_store_dwordx2 v[6:7], v[8:9]
	v_pk_mul_f32 v[8:9], v[48:49], v[4:5] op_sel_hi:[1,0]
	v_pk_mul_f32 v[10:11], v[50:51], v[4:5] op_sel_hi:[1,0]
	v_cvt_pk_bf16_f32 v8, v8, v9
	v_cvt_pk_bf16_f32 v9, v10, v11
	flat_store_dwordx2 v[6:7], v[8:9] offset:32
	v_pk_mul_f32 v[8:9], v[56:57], v[4:5] op_sel_hi:[1,0]
	v_pk_mul_f32 v[10:11], v[58:59], v[4:5] op_sel_hi:[1,0]
	v_cvt_pk_bf16_f32 v8, v8, v9
	v_cvt_pk_bf16_f32 v9, v10, v11
	flat_store_dwordx2 v[6:7], v[8:9] offset:64
	v_pk_mul_f32 v[8:9], v[60:61], v[4:5] op_sel_hi:[1,0]
	v_pk_mul_f32 v[4:5], v[62:63], v[4:5] op_sel_hi:[1,0]
	v_cvt_pk_bf16_f32 v8, v8, v9
	v_cvt_pk_bf16_f32 v9, v4, v5
	flat_store_dwordx2 v[6:7], v[8:9] offset:96
	s_waitcnt lgkmcnt(0)
	s_barrier
	s_and_saveexec_b64 s[6:7], s[4:5]
	s_cbranch_execz .LBB0_2955
	s_cmp_eq_u32 s32, 0
	s_cbranch_scc1 .Lqf5
	s_waitcnt vmcnt(0) lgkmcnt(0)
	ds_write_b32 v177, v253
	s_mov_b32 s32, 0
	s_branch .LBB0_2955
